# fixup phase: UB row load hoisted to the top of each iteration so its round trip overlaps the PB/GB/conv-weight loads
# speedup vs baseline: 1.0404x; 1.0065x over previous
.LBB0_156:
	s_or_b64 exec, exec, s[72:73]
	s_waitcnt vmcnt(0)
	v_mul_f32_e32 v8, 0xbfb8aa3b, v0
	v_exp_f32_e32 v8, v8
	s_movk_i32 s11, 0x1600
	v_add_u32_e32 v22, 0x4000, v22
	v_cmp_le_i32_e32 vcc, s10, v22
	v_add_f32_e32 v8, 1.0, v8
	v_rcp_f32_e32 v8, v8
	v_add_u32_e32 v23, 0x10000, v23
	s_or_b64 s[52:53], vcc, s[52:53]
	v_mul_f32_e32 v0, v0, v8
	v_mul_f32_e32 v0, v32, v0
	v_mul_f32_e32 v4, 0xbfb8aa3b, v1
	v_exp_f32_e32 v4, v4
	s_nop 0
	v_add_f32_e32 v4, 1.0, v4
	v_rcp_f32_e32 v4, v4
	s_nop 0
	v_mul_f32_e32 v1, v1, v4
	v_mul_f32_e32 v4, 0xbfb8aa3b, v2
	v_exp_f32_e32 v4, v4
	v_mul_f32_e32 v1, v33, v1
	s_nop 0
	v_cvt_pk_bf16_f32 v0, v0, v1
	s_nop 1
	v_add_f32_e32 v4, 1.0, v4
	v_rcp_f32_e32 v4, v4
	s_nop 0
	v_mul_f32_e32 v2, v2, v4
	v_mul_f32_e32 v4, 0xbfb8aa3b, v3
	v_exp_f32_e32 v4, v4
	v_mul_f32_e32 v2, v34, v2
	v_add_f32_e32 v4, 1.0, v4
	v_rcp_f32_e32 v4, v4
	s_nop 0
	v_mul_f32_e32 v3, v3, v4
	v_mul_f32_e32 v3, v35, v3
	s_nop 0
	v_cvt_pk_bf16_f32 v1, v2, v3
	s_nop 1
	v_lshl_or_b32 v4, v25, 6, v24
	v_mov_b64_e32 v[2:3], s[46:47]
	v_mad_i64_i32 v[2:3], s[30:31], v4, s11, v[2:3]
	v_lshl_add_u64 v[2:3], v[16:17], 1, v[2:3]
	global_store_dwordx2 v[2:3], v[0:1], off
	s_andn2_b64 exec, exec, s[52:53]
	s_cbranch_execz .LBB0_163
.LBB0_157:
	s_mov_b32 s11, 0x2e8ba2e9
	v_mul_hi_i32 v0, v22, s11
	s_waitcnt lgkmcnt(0)
	v_ashrrev_i32_e32 v1, 7, v0
	v_lshrrev_b32_e32 v2, 31, v0
	v_ashrrev_i32_e32 v0, 8, v0
	v_add_u32_e32 v1, v1, v2
	v_add_u32_e32 v25, v0, v2
	v_mul_i32_i24_e32 v3, 0x2c0, v1
	v_and_b32_e32 v24, 1, v1
	v_lshlrev_b32_e32 v26, 1, v25
	v_lshlrev_b32_e32 v3, 2, v3
	v_or_b32_e32 v0, v26, v24
	v_sub_u32_e32 v16, v23, v3
	v_mul_hi_i32_i24_e32 v19, 0xb00, v0
	v_mul_i32_i24_e32 v18, 0xb00, v0
	v_lshl_add_u64 v[0:1], v[18:19], 2, s[42:43]
	v_ashrrev_i32_e32 v17, 31, v16
	v_lshl_add_u64 v[0:1], v[16:17], 2, v[0:1]
	global_load_dwordx4 v[0:3], v[0:1], off
	v_lshl_add_u64 v[34:35], v[18:19], 2, s[44:45]
	v_lshl_add_u64 v[34:35], v[16:17], 2, v[34:35]
	global_load_dwordx4 v[32:35], v[34:35], off
	v_and_b32_e32 v4, 31, v25
	v_cmp_ne_u32_e32 vcc, 0, v4
	s_and_saveexec_b64 s[72:73], vcc
	s_cbranch_execz .LBB0_156
	v_add_u32_e32 v4, -1, v26
	v_mul_hi_i32_i24_e32 v5, 0x2c00, v4
	v_mul_i32_i24_e32 v4, 0x2c00, v4
	v_lshl_add_u64 v[4:5], s[40:41], 0, v[4:5]
	v_lshlrev_b64 v[20:21], 2, v[16:17]
	v_lshl_add_u64 v[4:5], v[4:5], 0, v[20:21]
	global_load_dwordx4 v[8:11], v[4:5], off
	v_lshl_add_u64 v[4:5], s[38:39], 0, v[20:21]
	global_load_dwordx4 v[4:7], v[4:5], off
	v_cmp_ne_u32_e32 vcc, 0, v24
	s_and_saveexec_b64 s[30:31], vcc
	s_xor_b64 s[74:75], exec, s[30:31]
	s_cbranch_execz .LBB0_160
	s_waitcnt vmcnt(0)
	v_pk_mul_f32 v[14:15], v[10:11], v[6:7]
	v_pk_mul_f32 v[12:13], v[8:9], v[4:5]
